# earlyinv2: XCD-leader path also issues its L1 invalidate early (with the release write-back); experimental
# baseline (speedup 1.0000x reference)
;   __host__ __device__ __forceinline__ unsigned* bar() const { return (unsigned*)(wsl() + OFF_BAR); }
; __device__ __forceinline__ unsigned xb_add(unsigned* p, unsigned v) { return __hip_atomic_fetch_add(p, v, __ATOMIC_RELAXED, __HIP_MEMORY_SCOPE_AGENT); }
; __device__ __forceinline__ void xcd_barrier(const XcdBarrier& b) {
;     ...
;         if (old + 1u == (gen + 1u) * nloc) {
;             __builtin_amdgcn_fence(__ATOMIC_RELEASE, "agent");
;             asm volatile("s_waitcnt vmcnt(0)" ::: "memory");
;             const unsigned og = xb_add(&bar[XB_TOP], 1u);
.LBB0_1105:
	s_andn2_saveexec_b64 s[2:3], s[4:5]
	s_cbranch_execz .LBB0_1125
	s_mov_b64 s[2:3], exec
	buffer_inv sc1
	buffer_wbl2 sc1
	s_waitcnt lgkmcnt(0)
	s_waitcnt vmcnt(0)
	v_mbcnt_lo_u32_b32 v1, s2, 0
	v_mbcnt_hi_u32_b32 v1, s3, v1
	v_cmp_eq_u32_e32 vcc, 0, v1
	s_and_saveexec_b64 s[4:5], vcc
	s_cbranch_execz .LBB0_1108
	s_bcnt1_i32_b64 s2, s[2:3]
	v_mov_b32_e32 v2, s2
	v_readlane_b32 s2, v255, 16
	v_readlane_b32 s3, v255, 17
	s_nop 4
	global_atomic_add v2, v167, v2, s[2:3] sc0

;   __host__ __device__ __forceinline__ unsigned* bar() const { return (unsigned*)(wsl() + OFF_BAR); }
; __device__ __forceinline__ unsigned xb_ld(unsigned* p)              { return __hip_atomic_load(p, __ATOMIC_RELAXED, __HIP_MEMORY_SCOPE_AGENT); }
; __device__ __forceinline__ unsigned xb_add(unsigned* p, unsigned v) { return __hip_atomic_fetch_add(p, v, __ATOMIC_RELAXED, __HIP_MEMORY_SCOPE_AGENT); }
; #define XB_SPIN(cond, bar) do { unsigned _sp = 0; while (cond) { __builtin_amdgcn_s_sleep(1); \
;     if ((++_sp & 255u) == 0u) { if (xb_ld(&(bar)[XB_TMO])) break; if (_sp > XB_SPIN_CAP) { atomicAdd(&(bar)[XB_TMO], 1u); break; } } } } while (0)
; __device__ __forceinline__ void xcd_barrier(const XcdBarrier& b) {
;     ...
;             else XB_SPIN(xb_ld(&bar[XB_TOPGEN]) == tg, bar);
;             __builtin_amdgcn_fence(__ATOMIC_ACQUIRE, "agent");
;             xb_add(&bar[XB_XGEN(b.x)], 1u);
.LBB0_1122:
	s_or_b64 exec, exec, s[2:3]
	s_mov_b64 s[2:3], exec
	v_mbcnt_lo_u32_b32 v0, s2, 0
	v_mbcnt_hi_u32_b32 v0, s3, v0
	v_cmp_eq_u32_e32 vcc, 0, v0
	s_waitcnt vmcnt(0)
	s_and_saveexec_b64 s[4:5], vcc
	s_cbranch_execz .LBB0_1124
	s_bcnt1_i32_b64 s2, s[2:3]
	v_mov_b32_e32 v0, s2
	v_readlane_b32 s2, v255, 14
	v_readlane_b32 s3, v255, 15
	s_nop 4
	global_atomic_add v167, v0, s[2:3]
